# strategy 4: one static s_setprio 1 for waves 4-7 (set once per layer-loop iteration, never lowered)
# speedup vs baseline: 1.0077x; 1.0026x over previous
; __global__ void __launch_bounds__(512) hybrid_megakernel(Params p) {
;     ...
;   for (int layer = 0; layer < DEPTH; ++layer) {
;     if (layer > 0) convert_weights(p, layer, lds, 2);
;     if (STOP_AFTER != 0 && STOP_AFTER == layer * 10) return;
;     phaseA(p, sl, layer, lds);
.LBB0_235:
	v_readfirstlane_b32 s0, v210
	s_nop 3
	s_lshr_b32 s0, s0, 6
	s_cmp_ge_u32 s0, 4
	s_cbranch_scc0 .Lmy_prio_done
	s_setprio 1
